# gemm_in sub-step (a): the B1 fragment reads are issued ahead of the W-refill barrier (barrier wait recounted to lgkmcnt(7)), so their LDS latency overlaps the barrier
# speedup vs baseline: 1.0019x; 1.0019x over previous
.Lgin_loop:
	s_waitcnt vmcnt(4)
	s_barrier
	ds_read_b128 v[230:233], v175 offset:0
	ds_read_b128 v[182:185], v176 offset:16384
	ds_read_b128 v[234:237], v175 offset:2048
	ds_read_b128 v[238:241], v175 offset:4096
	ds_read_b128 v[242:245], v175 offset:6144
	ds_read_b128 v[136:139], v177 offset:0
	ds_read_b128 v[140:143], v177 offset:2048
	ds_read_b128 v[144:147], v177 offset:4096
	ds_read_b128 v[148:151], v177 offset:6144
	ds_read_b128 v[186:189], v176 offset:18432
	ds_read_b128 v[190:193], v176 offset:20480
	ds_read_b128 v[194:197], v176 offset:22528
	s_add_u32 m0, s11, 0xc000
	s_waitcnt lgkmcnt(10)
	v_mfma_f32_16x16x32_f16 v[124:127], v[230:233], v[182:185], v[124:127]
	s_waitcnt lgkmcnt(9)
	v_mfma_f32_16x16x32_f16 v[92:95], v[234:237], v[182:185], v[92:95]
	s_waitcnt lgkmcnt(8)
	v_mfma_f32_16x16x32_f16 v[60:63], v[238:241], v[182:185], v[60:63]
	s_waitcnt lgkmcnt(7)
	v_mfma_f32_16x16x32_f16 v[28:31], v[242:245], v[182:185], v[28:31]
	global_load_lds_dwordx4 v128, s[6:7]
	ds_read_b128 v[198:201], v178 offset:16384
	ds_read_b128 v[202:205], v178 offset:18432
	ds_read_b128 v[222:225], v178 offset:20480
	ds_read_b128 v[226:229], v178 offset:22528
	s_waitcnt lgkmcnt(7)
	s_barrier
	s_add_u32 m0, s11, 0xd000
	s_waitcnt lgkmcnt(6)
	v_mfma_f32_16x16x32_f16 v[120:123], v[230:233], v[186:189], v[120:123]
	v_mfma_f32_16x16x32_f16 v[88:91], v[234:237], v[186:189], v[88:91]
	v_mfma_f32_16x16x32_f16 v[56:59], v[238:241], v[186:189], v[56:59]
	v_mfma_f32_16x16x32_f16 v[24:27], v[242:245], v[186:189], v[24:27]
	global_load_lds_dwordx4 v129, s[6:7]
	s_add_u32 m0, s11, 0xe000
	s_waitcnt lgkmcnt(5)
	v_mfma_f32_16x16x32_f16 v[116:119], v[230:233], v[190:193], v[116:119]
	v_mfma_f32_16x16x32_f16 v[84:87], v[234:237], v[190:193], v[84:87]
	v_mfma_f32_16x16x32_f16 v[52:55], v[238:241], v[190:193], v[52:55]
	v_mfma_f32_16x16x32_f16 v[20:23], v[242:245], v[190:193], v[20:23]
	global_load_lds_dwordx4 v132, s[6:7]
	s_add_u32 m0, s11, 0xf000
	s_waitcnt lgkmcnt(4)
	v_mfma_f32_16x16x32_f16 v[112:115], v[230:233], v[194:197], v[112:115]
	v_mfma_f32_16x16x32_f16 v[80:83], v[234:237], v[194:197], v[80:83]
	v_mfma_f32_16x16x32_f16 v[48:51], v[238:241], v[194:197], v[48:51]
	v_mfma_f32_16x16x32_f16 v[16:19], v[242:245], v[194:197], v[16:19]
	global_load_lds_dwordx4 v133, s[6:7]
	s_add_u32 m0, s11, 0x0
	s_waitcnt lgkmcnt(3)
	v_mfma_f32_16x16x32_f16 v[124:127], v[136:139], v[198:201], v[124:127]
	v_mfma_f32_16x16x32_f16 v[92:95], v[140:143], v[198:201], v[92:95]
	v_mfma_f32_16x16x32_f16 v[60:63], v[144:147], v[198:201], v[60:63]
	v_mfma_f32_16x16x32_f16 v[28:31], v[148:151], v[198:201], v[28:31]
	global_load_lds_dwordx4 v128, s[4:5]
	s_add_u32 m0, s11, 0x1000
	s_waitcnt lgkmcnt(2)
	v_mfma_f32_16x16x32_f16 v[120:123], v[136:139], v[202:205], v[120:123]
	v_mfma_f32_16x16x32_f16 v[88:91], v[140:143], v[202:205], v[88:91]
	v_mfma_f32_16x16x32_f16 v[56:59], v[144:147], v[202:205], v[56:59]
	v_mfma_f32_16x16x32_f16 v[24:27], v[148:151], v[202:205], v[24:27]
	global_load_lds_dwordx4 v129, s[4:5]
	s_add_u32 m0, s11, 0x2000
	s_waitcnt lgkmcnt(1)
	v_mfma_f32_16x16x32_f16 v[116:119], v[136:139], v[222:225], v[116:119]
	v_mfma_f32_16x16x32_f16 v[84:87], v[140:143], v[222:225], v[84:87]
	v_mfma_f32_16x16x32_f16 v[52:55], v[144:147], v[222:225], v[52:55]
	v_mfma_f32_16x16x32_f16 v[20:23], v[148:151], v[222:225], v[20:23]
	global_load_lds_dwordx4 v130, s[4:5]
	s_add_u32 m0, s11, 0x3000
	s_waitcnt lgkmcnt(0)
	v_mfma_f32_16x16x32_f16 v[112:115], v[136:139], v[226:229], v[112:115]
	v_mfma_f32_16x16x32_f16 v[80:83], v[140:143], v[226:229], v[80:83]
	v_mfma_f32_16x16x32_f16 v[48:51], v[144:147], v[226:229], v[48:51]
	v_mfma_f32_16x16x32_f16 v[16:19], v[148:151], v[226:229], v[16:19]
	global_load_lds_dwordx4 v131, s[4:5]
	s_add_u32 s6, s6, 128
	s_addc_u32 s7, s7, 0
	s_add_u32 s4, s4, 128
	s_addc_u32 s5, s5, 0
	s_waitcnt vmcnt(8)
	s_barrier
	ds_read_b128 v[182:185], v176 offset:32768
	ds_read_b128 v[186:189], v176 offset:34816
	ds_read_b128 v[190:193], v176 offset:36864
	ds_read_b128 v[194:197], v176 offset:38912
	ds_read_b128 v[198:201], v178 offset:32768
	ds_read_b128 v[202:205], v178 offset:34816
	ds_read_b128 v[222:225], v178 offset:36864
	ds_read_b128 v[226:229], v178 offset:38912
	s_add_u32 m0, s11, 0x4000
	s_waitcnt lgkmcnt(7)
	v_mfma_f32_16x16x32_f16 v[108:111], v[230:233], v[182:185], v[108:111]
	v_mfma_f32_16x16x32_f16 v[76:79], v[234:237], v[182:185], v[76:79]
	v_mfma_f32_16x16x32_f16 v[44:47], v[238:241], v[182:185], v[44:47]
	v_mfma_f32_16x16x32_f16 v[12:15], v[242:245], v[182:185], v[12:15]
	global_load_lds_dwordx4 v128, s[18:19]
	s_add_u32 m0, s11, 0x5000
	s_waitcnt lgkmcnt(6)
	v_mfma_f32_16x16x32_f16 v[104:107], v[230:233], v[186:189], v[104:107]
	v_mfma_f32_16x16x32_f16 v[72:75], v[234:237], v[186:189], v[72:75]
	v_mfma_f32_16x16x32_f16 v[40:43], v[238:241], v[186:189], v[40:43]
	v_mfma_f32_16x16x32_f16 v[8:11], v[242:245], v[186:189], v[8:11]
	global_load_lds_dwordx4 v129, s[18:19]
	s_add_u32 m0, s11, 0x6000
	s_waitcnt lgkmcnt(5)
	v_mfma_f32_16x16x32_f16 v[100:103], v[230:233], v[190:193], v[100:103]
	v_mfma_f32_16x16x32_f16 v[68:71], v[234:237], v[190:193], v[68:71]
	v_mfma_f32_16x16x32_f16 v[36:39], v[238:241], v[190:193], v[36:39]
	v_mfma_f32_16x16x32_f16 v[4:7], v[242:245], v[190:193], v[4:7]
	global_load_lds_dwordx4 v132, s[18:19]
	s_add_u32 m0, s11, 0x7000
	s_waitcnt lgkmcnt(4)
	v_mfma_f32_16x16x32_f16 v[96:99], v[230:233], v[194:197], v[96:99]
	v_mfma_f32_16x16x32_f16 v[64:67], v[234:237], v[194:197], v[64:67]
	v_mfma_f32_16x16x32_f16 v[32:35], v[238:241], v[194:197], v[32:35]
	v_mfma_f32_16x16x32_f16 v[0:3], v[242:245], v[194:197], v[0:3]
	global_load_lds_dwordx4 v133, s[18:19]
	s_waitcnt lgkmcnt(3)
	v_mfma_f32_16x16x32_f16 v[108:111], v[136:139], v[198:201], v[108:111]
	v_mfma_f32_16x16x32_f16 v[76:79], v[140:143], v[198:201], v[76:79]
	v_mfma_f32_16x16x32_f16 v[44:47], v[144:147], v[198:201], v[44:47]
	v_mfma_f32_16x16x32_f16 v[12:15], v[148:151], v[198:201], v[12:15]
	s_waitcnt lgkmcnt(2)
	v_mfma_f32_16x16x32_f16 v[104:107], v[136:139], v[202:205], v[104:107]
	v_mfma_f32_16x16x32_f16 v[72:75], v[140:143], v[202:205], v[72:75]
	v_mfma_f32_16x16x32_f16 v[40:43], v[144:147], v[202:205], v[40:43]
	v_mfma_f32_16x16x32_f16 v[8:11], v[148:151], v[202:205], v[8:11]
	s_waitcnt lgkmcnt(1)
	v_mfma_f32_16x16x32_f16 v[100:103], v[136:139], v[222:225], v[100:103]
	v_mfma_f32_16x16x32_f16 v[68:71], v[140:143], v[222:225], v[68:71]
	v_mfma_f32_16x16x32_f16 v[36:39], v[144:147], v[222:225], v[36:39]
	v_mfma_f32_16x16x32_f16 v[4:7], v[148:151], v[222:225], v[4:7]
	s_waitcnt lgkmcnt(0)
	v_mfma_f32_16x16x32_f16 v[96:99], v[136:139], v[226:229], v[96:99]
	v_mfma_f32_16x16x32_f16 v[64:67], v[140:143], v[226:229], v[64:67]
	v_mfma_f32_16x16x32_f16 v[32:35], v[144:147], v[226:229], v[32:35]
	v_mfma_f32_16x16x32_f16 v[0:3], v[148:151], v[226:229], v[0:3]
	s_add_u32 s18, s18, 128
	s_addc_u32 s19, s19, 0
	s_waitcnt vmcnt(4)
	s_barrier
	ds_read_b128 v[230:233], v175 offset:0
	ds_read_b128 v[182:185], v176 offset:49152
	ds_read_b128 v[234:237], v175 offset:2048
	ds_read_b128 v[238:241], v175 offset:4096
	ds_read_b128 v[242:245], v175 offset:6144
	ds_read_b128 v[136:139], v177 offset:0
	ds_read_b128 v[140:143], v177 offset:2048
	ds_read_b128 v[144:147], v177 offset:4096
	ds_read_b128 v[148:151], v177 offset:6144
	ds_read_b128 v[186:189], v176 offset:51200
	ds_read_b128 v[190:193], v176 offset:53248
	ds_read_b128 v[194:197], v176 offset:55296
	s_add_u32 m0, s11, 0x8000
	s_waitcnt lgkmcnt(10)
	v_mfma_f32_16x16x32_f16 v[124:127], v[230:233], v[182:185], v[124:127]
	s_waitcnt lgkmcnt(9)
	v_mfma_f32_16x16x32_f16 v[92:95], v[234:237], v[182:185], v[92:95]
	s_waitcnt lgkmcnt(8)
	v_mfma_f32_16x16x32_f16 v[60:63], v[238:241], v[182:185], v[60:63]
	s_waitcnt lgkmcnt(7)
	v_mfma_f32_16x16x32_f16 v[28:31], v[242:245], v[182:185], v[28:31]
	global_load_lds_dwordx4 v128, s[6:7]
	ds_read_b128 v[198:201], v178 offset:49152
	ds_read_b128 v[202:205], v178 offset:51200
	ds_read_b128 v[222:225], v178 offset:53248
	ds_read_b128 v[226:229], v178 offset:55296
	s_waitcnt lgkmcnt(7)
	s_barrier
	s_add_u32 m0, s11, 0x9000
	s_waitcnt lgkmcnt(6)
	v_mfma_f32_16x16x32_f16 v[120:123], v[230:233], v[186:189], v[120:123]
	v_mfma_f32_16x16x32_f16 v[88:91], v[234:237], v[186:189], v[88:91]
	v_mfma_f32_16x16x32_f16 v[56:59], v[238:241], v[186:189], v[56:59]
	v_mfma_f32_16x16x32_f16 v[24:27], v[242:245], v[186:189], v[24:27]
	global_load_lds_dwordx4 v129, s[6:7]
	s_add_u32 m0, s11, 0xa000
	s_waitcnt lgkmcnt(5)
	v_mfma_f32_16x16x32_f16 v[116:119], v[230:233], v[190:193], v[116:119]
	v_mfma_f32_16x16x32_f16 v[84:87], v[234:237], v[190:193], v[84:87]
	v_mfma_f32_16x16x32_f16 v[52:55], v[238:241], v[190:193], v[52:55]
	v_mfma_f32_16x16x32_f16 v[20:23], v[242:245], v[190:193], v[20:23]
	global_load_lds_dwordx4 v132, s[6:7]
	s_add_u32 m0, s11, 0xb000
	s_waitcnt lgkmcnt(4)
	v_mfma_f32_16x16x32_f16 v[112:115], v[230:233], v[194:197], v[112:115]
	v_mfma_f32_16x16x32_f16 v[80:83], v[234:237], v[194:197], v[80:83]
	v_mfma_f32_16x16x32_f16 v[48:51], v[238:241], v[194:197], v[48:51]
	v_mfma_f32_16x16x32_f16 v[16:19], v[242:245], v[194:197], v[16:19]
	global_load_lds_dwordx4 v133, s[6:7]
	s_add_u32 m0, s11, 0x0
	s_waitcnt lgkmcnt(3)
	v_mfma_f32_16x16x32_f16 v[124:127], v[136:139], v[198:201], v[124:127]
	v_mfma_f32_16x16x32_f16 v[92:95], v[140:143], v[198:201], v[92:95]
	v_mfma_f32_16x16x32_f16 v[60:63], v[144:147], v[198:201], v[60:63]
	v_mfma_f32_16x16x32_f16 v[28:31], v[148:151], v[198:201], v[28:31]
	global_load_lds_dwordx4 v128, s[4:5]
	s_add_u32 m0, s11, 0x1000
	s_waitcnt lgkmcnt(2)
	v_mfma_f32_16x16x32_f16 v[120:123], v[136:139], v[202:205], v[120:123]
	v_mfma_f32_16x16x32_f16 v[88:91], v[140:143], v[202:205], v[88:91]
	v_mfma_f32_16x16x32_f16 v[56:59], v[144:147], v[202:205], v[56:59]
	v_mfma_f32_16x16x32_f16 v[24:27], v[148:151], v[202:205], v[24:27]
	global_load_lds_dwordx4 v129, s[4:5]
	s_add_u32 m0, s11, 0x2000
	s_waitcnt lgkmcnt(1)
	v_mfma_f32_16x16x32_f16 v[116:119], v[136:139], v[222:225], v[116:119]
	v_mfma_f32_16x16x32_f16 v[84:87], v[140:143], v[222:225], v[84:87]
	v_mfma_f32_16x16x32_f16 v[52:55], v[144:147], v[222:225], v[52:55]
	v_mfma_f32_16x16x32_f16 v[20:23], v[148:151], v[222:225], v[20:23]
	global_load_lds_dwordx4 v130, s[4:5]
	s_add_u32 m0, s11, 0x3000
	s_waitcnt lgkmcnt(0)
	v_mfma_f32_16x16x32_f16 v[112:115], v[136:139], v[226:229], v[112:115]
	v_mfma_f32_16x16x32_f16 v[80:83], v[140:143], v[226:229], v[80:83]
	v_mfma_f32_16x16x32_f16 v[48:51], v[144:147], v[226:229], v[48:51]
	v_mfma_f32_16x16x32_f16 v[16:19], v[148:151], v[226:229], v[16:19]
	global_load_lds_dwordx4 v131, s[4:5]
	s_add_u32 s6, s6, 128
	s_addc_u32 s7, s7, 0
	s_add_u32 s4, s4, 128
	s_addc_u32 s5, s5, 0
	s_waitcnt vmcnt(8)
	s_barrier
	ds_read_b128 v[182:185], v176 offset:16384
	ds_read_b128 v[186:189], v176 offset:18432
	ds_read_b128 v[190:193], v176 offset:20480
	ds_read_b128 v[194:197], v176 offset:22528
	ds_read_b128 v[198:201], v178 offset:16384
	ds_read_b128 v[202:205], v178 offset:18432
	ds_read_b128 v[222:225], v178 offset:20480
	ds_read_b128 v[226:229], v178 offset:22528
	s_add_u32 m0, s11, 0xc000
	s_waitcnt lgkmcnt(7)
	v_mfma_f32_16x16x32_f16 v[108:111], v[230:233], v[182:185], v[108:111]
	v_mfma_f32_16x16x32_f16 v[76:79], v[234:237], v[182:185], v[76:79]
	v_mfma_f32_16x16x32_f16 v[44:47], v[238:241], v[182:185], v[44:47]
	v_mfma_f32_16x16x32_f16 v[12:15], v[242:245], v[182:185], v[12:15]
	global_load_lds_dwordx4 v128, s[18:19]
	s_add_u32 m0, s11, 0xd000
	s_waitcnt lgkmcnt(6)
	v_mfma_f32_16x16x32_f16 v[104:107], v[230:233], v[186:189], v[104:107]
	v_mfma_f32_16x16x32_f16 v[72:75], v[234:237], v[186:189], v[72:75]
	v_mfma_f32_16x16x32_f16 v[40:43], v[238:241], v[186:189], v[40:43]
	v_mfma_f32_16x16x32_f16 v[8:11], v[242:245], v[186:189], v[8:11]
	global_load_lds_dwordx4 v129, s[18:19]
	s_add_u32 m0, s11, 0xe000
	s_waitcnt lgkmcnt(5)
	v_mfma_f32_16x16x32_f16 v[100:103], v[230:233], v[190:193], v[100:103]
	v_mfma_f32_16x16x32_f16 v[68:71], v[234:237], v[190:193], v[68:71]
	v_mfma_f32_16x16x32_f16 v[36:39], v[238:241], v[190:193], v[36:39]
	v_mfma_f32_16x16x32_f16 v[4:7], v[242:245], v[190:193], v[4:7]
	global_load_lds_dwordx4 v132, s[18:19]
	s_add_u32 m0, s11, 0xf000
	s_waitcnt lgkmcnt(4)
	v_mfma_f32_16x16x32_f16 v[96:99], v[230:233], v[194:197], v[96:99]
	v_mfma_f32_16x16x32_f16 v[64:67], v[234:237], v[194:197], v[64:67]
	v_mfma_f32_16x16x32_f16 v[32:35], v[238:241], v[194:197], v[32:35]
	v_mfma_f32_16x16x32_f16 v[0:3], v[242:245], v[194:197], v[0:3]
	global_load_lds_dwordx4 v133, s[18:19]
	s_waitcnt lgkmcnt(3)
	v_mfma_f32_16x16x32_f16 v[108:111], v[136:139], v[198:201], v[108:111]
	v_mfma_f32_16x16x32_f16 v[76:79], v[140:143], v[198:201], v[76:79]
	v_mfma_f32_16x16x32_f16 v[44:47], v[144:147], v[198:201], v[44:47]
	v_mfma_f32_16x16x32_f16 v[12:15], v[148:151], v[198:201], v[12:15]
	s_waitcnt lgkmcnt(2)
	v_mfma_f32_16x16x32_f16 v[104:107], v[136:139], v[202:205], v[104:107]
	v_mfma_f32_16x16x32_f16 v[72:75], v[140:143], v[202:205], v[72:75]
	v_mfma_f32_16x16x32_f16 v[40:43], v[144:147], v[202:205], v[40:43]
	v_mfma_f32_16x16x32_f16 v[8:11], v[148:151], v[202:205], v[8:11]
	s_waitcnt lgkmcnt(1)
	v_mfma_f32_16x16x32_f16 v[100:103], v[136:139], v[222:225], v[100:103]
	v_mfma_f32_16x16x32_f16 v[68:71], v[140:143], v[222:225], v[68:71]
	v_mfma_f32_16x16x32_f16 v[36:39], v[144:147], v[222:225], v[36:39]
	v_mfma_f32_16x16x32_f16 v[4:7], v[148:151], v[222:225], v[4:7]
	s_waitcnt lgkmcnt(0)
	v_mfma_f32_16x16x32_f16 v[96:99], v[136:139], v[226:229], v[96:99]
	v_mfma_f32_16x16x32_f16 v[64:67], v[140:143], v[226:229], v[64:67]
	v_mfma_f32_16x16x32_f16 v[32:35], v[144:147], v[226:229], v[32:35]
	v_mfma_f32_16x16x32_f16 v[0:3], v[148:151], v[226:229], v[0:3]
	s_add_u32 s18, s18, 128
	s_addc_u32 s19, s19, 0
	s_waitcnt vmcnt(4)
	s_barrier
	ds_read_b128 v[230:233], v175 offset:0
	ds_read_b128 v[182:185], v176 offset:32768
	ds_read_b128 v[234:237], v175 offset:2048
	ds_read_b128 v[238:241], v175 offset:4096
	ds_read_b128 v[242:245], v175 offset:6144
	ds_read_b128 v[136:139], v177 offset:0
	ds_read_b128 v[140:143], v177 offset:2048
	ds_read_b128 v[144:147], v177 offset:4096
	ds_read_b128 v[148:151], v177 offset:6144
	ds_read_b128 v[186:189], v176 offset:34816
	ds_read_b128 v[190:193], v176 offset:36864
	ds_read_b128 v[194:197], v176 offset:38912
	s_add_u32 m0, s11, 0x4000
	s_waitcnt lgkmcnt(10)
	v_mfma_f32_16x16x32_f16 v[124:127], v[230:233], v[182:185], v[124:127]
	s_waitcnt lgkmcnt(9)
	v_mfma_f32_16x16x32_f16 v[92:95], v[234:237], v[182:185], v[92:95]
	s_waitcnt lgkmcnt(8)
	v_mfma_f32_16x16x32_f16 v[60:63], v[238:241], v[182:185], v[60:63]
	s_waitcnt lgkmcnt(7)
	v_mfma_f32_16x16x32_f16 v[28:31], v[242:245], v[182:185], v[28:31]
	global_load_lds_dwordx4 v128, s[6:7]
	ds_read_b128 v[198:201], v178 offset:32768
	ds_read_b128 v[202:205], v178 offset:34816
	ds_read_b128 v[222:225], v178 offset:36864
	ds_read_b128 v[226:229], v178 offset:38912
	s_waitcnt lgkmcnt(7)
	s_barrier
	s_add_u32 m0, s11, 0x5000
	s_waitcnt lgkmcnt(6)
	v_mfma_f32_16x16x32_f16 v[120:123], v[230:233], v[186:189], v[120:123]
	v_mfma_f32_16x16x32_f16 v[88:91], v[234:237], v[186:189], v[88:91]
	v_mfma_f32_16x16x32_f16 v[56:59], v[238:241], v[186:189], v[56:59]
	v_mfma_f32_16x16x32_f16 v[24:27], v[242:245], v[186:189], v[24:27]
	global_load_lds_dwordx4 v129, s[6:7]
	s_add_u32 m0, s11, 0x6000
	s_waitcnt lgkmcnt(5)
	v_mfma_f32_16x16x32_f16 v[116:119], v[230:233], v[190:193], v[116:119]
	v_mfma_f32_16x16x32_f16 v[84:87], v[234:237], v[190:193], v[84:87]
	v_mfma_f32_16x16x32_f16 v[52:55], v[238:241], v[190:193], v[52:55]
	v_mfma_f32_16x16x32_f16 v[20:23], v[242:245], v[190:193], v[20:23]
	global_load_lds_dwordx4 v132, s[6:7]
	s_add_u32 m0, s11, 0x7000
	s_waitcnt lgkmcnt(4)
	v_mfma_f32_16x16x32_f16 v[112:115], v[230:233], v[194:197], v[112:115]
	v_mfma_f32_16x16x32_f16 v[80:83], v[234:237], v[194:197], v[80:83]
	v_mfma_f32_16x16x32_f16 v[48:51], v[238:241], v[194:197], v[48:51]
	v_mfma_f32_16x16x32_f16 v[16:19], v[242:245], v[194:197], v[16:19]
	global_load_lds_dwordx4 v133, s[6:7]
	s_add_u32 m0, s11, 0x0
	s_waitcnt lgkmcnt(3)
	v_mfma_f32_16x16x32_f16 v[124:127], v[136:139], v[198:201], v[124:127]
	v_mfma_f32_16x16x32_f16 v[92:95], v[140:143], v[198:201], v[92:95]
	v_mfma_f32_16x16x32_f16 v[60:63], v[144:147], v[198:201], v[60:63]
	v_mfma_f32_16x16x32_f16 v[28:31], v[148:151], v[198:201], v[28:31]
	global_load_lds_dwordx4 v128, s[4:5]
	s_add_u32 m0, s11, 0x1000
	s_waitcnt lgkmcnt(2)
	v_mfma_f32_16x16x32_f16 v[120:123], v[136:139], v[202:205], v[120:123]
	v_mfma_f32_16x16x32_f16 v[88:91], v[140:143], v[202:205], v[88:91]
	v_mfma_f32_16x16x32_f16 v[56:59], v[144:147], v[202:205], v[56:59]
	v_mfma_f32_16x16x32_f16 v[24:27], v[148:151], v[202:205], v[24:27]
	global_load_lds_dwordx4 v129, s[4:5]
	s_add_u32 m0, s11, 0x2000
	s_waitcnt lgkmcnt(1)
	v_mfma_f32_16x16x32_f16 v[116:119], v[136:139], v[222:225], v[116:119]
	v_mfma_f32_16x16x32_f16 v[84:87], v[140:143], v[222:225], v[84:87]
	v_mfma_f32_16x16x32_f16 v[52:55], v[144:147], v[222:225], v[52:55]
	v_mfma_f32_16x16x32_f16 v[20:23], v[148:151], v[222:225], v[20:23]
	global_load_lds_dwordx4 v130, s[4:5]
	s_add_u32 m0, s11, 0x3000
	s_waitcnt lgkmcnt(0)
	v_mfma_f32_16x16x32_f16 v[112:115], v[136:139], v[226:229], v[112:115]
	v_mfma_f32_16x16x32_f16 v[80:83], v[140:143], v[226:229], v[80:83]
	v_mfma_f32_16x16x32_f16 v[48:51], v[144:147], v[226:229], v[48:51]
	v_mfma_f32_16x16x32_f16 v[16:19], v[148:151], v[226:229], v[16:19]
	global_load_lds_dwordx4 v131, s[4:5]
	s_add_u32 s6, s6, 128
	s_addc_u32 s7, s7, 0
	s_add_u32 s4, s4, 128
	s_addc_u32 s5, s5, 0
	s_waitcnt vmcnt(8)
	s_barrier
	ds_read_b128 v[182:185], v176 offset:49152
	ds_read_b128 v[186:189], v176 offset:51200
	ds_read_b128 v[190:193], v176 offset:53248
	ds_read_b128 v[194:197], v176 offset:55296
	ds_read_b128 v[198:201], v178 offset:49152
	ds_read_b128 v[202:205], v178 offset:51200
	ds_read_b128 v[222:225], v178 offset:53248
	ds_read_b128 v[226:229], v178 offset:55296
	s_add_u32 m0, s11, 0x8000
	s_waitcnt lgkmcnt(7)
	v_mfma_f32_16x16x32_f16 v[108:111], v[230:233], v[182:185], v[108:111]
	v_mfma_f32_16x16x32_f16 v[76:79], v[234:237], v[182:185], v[76:79]
	v_mfma_f32_16x16x32_f16 v[44:47], v[238:241], v[182:185], v[44:47]
	v_mfma_f32_16x16x32_f16 v[12:15], v[242:245], v[182:185], v[12:15]
	global_load_lds_dwordx4 v128, s[18:19]
	s_add_u32 m0, s11, 0x9000
	s_waitcnt lgkmcnt(6)
	v_mfma_f32_16x16x32_f16 v[104:107], v[230:233], v[186:189], v[104:107]
	v_mfma_f32_16x16x32_f16 v[72:75], v[234:237], v[186:189], v[72:75]
	v_mfma_f32_16x16x32_f16 v[40:43], v[238:241], v[186:189], v[40:43]
	v_mfma_f32_16x16x32_f16 v[8:11], v[242:245], v[186:189], v[8:11]
	global_load_lds_dwordx4 v129, s[18:19]
	s_add_u32 m0, s11, 0xa000
	s_waitcnt lgkmcnt(5)
	v_mfma_f32_16x16x32_f16 v[100:103], v[230:233], v[190:193], v[100:103]
	v_mfma_f32_16x16x32_f16 v[68:71], v[234:237], v[190:193], v[68:71]
	v_mfma_f32_16x16x32_f16 v[36:39], v[238:241], v[190:193], v[36:39]
	v_mfma_f32_16x16x32_f16 v[4:7], v[242:245], v[190:193], v[4:7]
	global_load_lds_dwordx4 v132, s[18:19]
	s_add_u32 m0, s11, 0xb000
	s_waitcnt lgkmcnt(4)
	v_mfma_f32_16x16x32_f16 v[96:99], v[230:233], v[194:197], v[96:99]
	v_mfma_f32_16x16x32_f16 v[64:67], v[234:237], v[194:197], v[64:67]
	v_mfma_f32_16x16x32_f16 v[32:35], v[238:241], v[194:197], v[32:35]
	v_mfma_f32_16x16x32_f16 v[0:3], v[242:245], v[194:197], v[0:3]
	global_load_lds_dwordx4 v133, s[18:19]
	s_waitcnt lgkmcnt(3)
	v_mfma_f32_16x16x32_f16 v[108:111], v[136:139], v[198:201], v[108:111]
	v_mfma_f32_16x16x32_f16 v[76:79], v[140:143], v[198:201], v[76:79]
	v_mfma_f32_16x16x32_f16 v[44:47], v[144:147], v[198:201], v[44:47]
	v_mfma_f32_16x16x32_f16 v[12:15], v[148:151], v[198:201], v[12:15]
	s_waitcnt lgkmcnt(2)
	v_mfma_f32_16x16x32_f16 v[104:107], v[136:139], v[202:205], v[104:107]
	v_mfma_f32_16x16x32_f16 v[72:75], v[140:143], v[202:205], v[72:75]
	v_mfma_f32_16x16x32_f16 v[40:43], v[144:147], v[202:205], v[40:43]
	v_mfma_f32_16x16x32_f16 v[8:11], v[148:151], v[202:205], v[8:11]
	s_waitcnt lgkmcnt(1)
	v_mfma_f32_16x16x32_f16 v[100:103], v[136:139], v[222:225], v[100:103]
	v_mfma_f32_16x16x32_f16 v[68:71], v[140:143], v[222:225], v[68:71]
	v_mfma_f32_16x16x32_f16 v[36:39], v[144:147], v[222:225], v[36:39]
	v_mfma_f32_16x16x32_f16 v[4:7], v[148:151], v[222:225], v[4:7]
	s_waitcnt lgkmcnt(0)
	v_mfma_f32_16x16x32_f16 v[96:99], v[136:139], v[226:229], v[96:99]
	v_mfma_f32_16x16x32_f16 v[64:67], v[140:143], v[226:229], v[64:67]
	v_mfma_f32_16x16x32_f16 v[32:35], v[144:147], v[226:229], v[32:35]
	v_mfma_f32_16x16x32_f16 v[0:3], v[148:151], v[226:229], v[0:3]
	s_add_u32 s18, s18, 128
	s_addc_u32 s19, s19, 0
	s_add_i32 s10, s10, 1
	s_cmp_lt_u32 s10, 10
	s_cbranch_scc1 .Lgin_loop
	s_waitcnt vmcnt(4)
	s_barrier
	ds_read_b128 v[230:233], v175 offset:0
	ds_read_b128 v[182:185], v176 offset:16384
	ds_read_b128 v[234:237], v175 offset:2048
	ds_read_b128 v[238:241], v175 offset:4096
	ds_read_b128 v[242:245], v175 offset:6144
	ds_read_b128 v[136:139], v177 offset:0
	ds_read_b128 v[140:143], v177 offset:2048
	ds_read_b128 v[144:147], v177 offset:4096
	ds_read_b128 v[148:151], v177 offset:6144
	ds_read_b128 v[186:189], v176 offset:18432
	ds_read_b128 v[190:193], v176 offset:20480
	ds_read_b128 v[194:197], v176 offset:22528
	s_add_u32 m0, s11, 0xc000
	s_waitcnt lgkmcnt(10)
	v_mfma_f32_16x16x32_f16 v[124:127], v[230:233], v[182:185], v[124:127]
	s_waitcnt lgkmcnt(9)
	v_mfma_f32_16x16x32_f16 v[92:95], v[234:237], v[182:185], v[92:95]
	s_waitcnt lgkmcnt(8)
	v_mfma_f32_16x16x32_f16 v[60:63], v[238:241], v[182:185], v[60:63]
	s_waitcnt lgkmcnt(7)
	v_mfma_f32_16x16x32_f16 v[28:31], v[242:245], v[182:185], v[28:31]
	global_load_lds_dwordx4 v128, s[6:7]
	ds_read_b128 v[198:201], v178 offset:16384
	ds_read_b128 v[202:205], v178 offset:18432
	ds_read_b128 v[222:225], v178 offset:20480
	ds_read_b128 v[226:229], v178 offset:22528
	s_waitcnt lgkmcnt(7)
	s_barrier
	s_add_u32 m0, s11, 0xd000
	s_waitcnt lgkmcnt(6)
	v_mfma_f32_16x16x32_f16 v[120:123], v[230:233], v[186:189], v[120:123]
	v_mfma_f32_16x16x32_f16 v[88:91], v[234:237], v[186:189], v[88:91]
	v_mfma_f32_16x16x32_f16 v[56:59], v[238:241], v[186:189], v[56:59]
	v_mfma_f32_16x16x32_f16 v[24:27], v[242:245], v[186:189], v[24:27]
	global_load_lds_dwordx4 v129, s[6:7]
	s_add_u32 m0, s11, 0xe000
	s_waitcnt lgkmcnt(5)
	v_mfma_f32_16x16x32_f16 v[116:119], v[230:233], v[190:193], v[116:119]
	v_mfma_f32_16x16x32_f16 v[84:87], v[234:237], v[190:193], v[84:87]
	v_mfma_f32_16x16x32_f16 v[52:55], v[238:241], v[190:193], v[52:55]
	v_mfma_f32_16x16x32_f16 v[20:23], v[242:245], v[190:193], v[20:23]
	global_load_lds_dwordx4 v132, s[6:7]
	s_add_u32 m0, s11, 0xf000
	s_waitcnt lgkmcnt(4)
	v_mfma_f32_16x16x32_f16 v[112:115], v[230:233], v[194:197], v[112:115]
	v_mfma_f32_16x16x32_f16 v[80:83], v[234:237], v[194:197], v[80:83]
	v_mfma_f32_16x16x32_f16 v[48:51], v[238:241], v[194:197], v[48:51]
	v_mfma_f32_16x16x32_f16 v[16:19], v[242:245], v[194:197], v[16:19]
	global_load_lds_dwordx4 v133, s[6:7]
	s_add_u32 m0, s11, 0x0
	s_waitcnt lgkmcnt(3)
	v_mfma_f32_16x16x32_f16 v[124:127], v[136:139], v[198:201], v[124:127]
	v_mfma_f32_16x16x32_f16 v[92:95], v[140:143], v[198:201], v[92:95]
	v_mfma_f32_16x16x32_f16 v[60:63], v[144:147], v[198:201], v[60:63]
	v_mfma_f32_16x16x32_f16 v[28:31], v[148:151], v[198:201], v[28:31]
	global_load_lds_dwordx4 v128, s[4:5]
	s_add_u32 m0, s11, 0x1000
	s_waitcnt lgkmcnt(2)
	v_mfma_f32_16x16x32_f16 v[120:123], v[136:139], v[202:205], v[120:123]
	v_mfma_f32_16x16x32_f16 v[88:91], v[140:143], v[202:205], v[88:91]
	v_mfma_f32_16x16x32_f16 v[56:59], v[144:147], v[202:205], v[56:59]
	v_mfma_f32_16x16x32_f16 v[24:27], v[148:151], v[202:205], v[24:27]
	global_load_lds_dwordx4 v129, s[4:5]
	s_add_u32 m0, s11, 0x2000
	s_waitcnt lgkmcnt(1)
	v_mfma_f32_16x16x32_f16 v[116:119], v[136:139], v[222:225], v[116:119]
	v_mfma_f32_16x16x32_f16 v[84:87], v[140:143], v[222:225], v[84:87]
	v_mfma_f32_16x16x32_f16 v[52:55], v[144:147], v[222:225], v[52:55]
	v_mfma_f32_16x16x32_f16 v[20:23], v[148:151], v[222:225], v[20:23]
	global_load_lds_dwordx4 v130, s[4:5]
	s_add_u32 m0, s11, 0x3000
	s_waitcnt lgkmcnt(0)
	v_mfma_f32_16x16x32_f16 v[112:115], v[136:139], v[226:229], v[112:115]
	v_mfma_f32_16x16x32_f16 v[80:83], v[140:143], v[226:229], v[80:83]
	v_mfma_f32_16x16x32_f16 v[48:51], v[144:147], v[226:229], v[48:51]
	v_mfma_f32_16x16x32_f16 v[16:19], v[148:151], v[226:229], v[16:19]
	global_load_lds_dwordx4 v131, s[4:5]
	s_add_u32 s6, s6, 128
	s_addc_u32 s7, s7, 0
	s_add_u32 s4, s4, 128
	s_addc_u32 s5, s5, 0
	s_waitcnt vmcnt(8)
	s_barrier
	ds_read_b128 v[182:185], v176 offset:32768
	ds_read_b128 v[186:189], v176 offset:34816
	ds_read_b128 v[190:193], v176 offset:36864
	ds_read_b128 v[194:197], v176 offset:38912
	ds_read_b128 v[198:201], v178 offset:32768
	ds_read_b128 v[202:205], v178 offset:34816
	ds_read_b128 v[222:225], v178 offset:36864
	ds_read_b128 v[226:229], v178 offset:38912
	s_add_u32 m0, s11, 0x4000
	s_waitcnt lgkmcnt(7)
	v_mfma_f32_16x16x32_f16 v[108:111], v[230:233], v[182:185], v[108:111]
	v_mfma_f32_16x16x32_f16 v[76:79], v[234:237], v[182:185], v[76:79]
	v_mfma_f32_16x16x32_f16 v[44:47], v[238:241], v[182:185], v[44:47]
	v_mfma_f32_16x16x32_f16 v[12:15], v[242:245], v[182:185], v[12:15]
	global_load_lds_dwordx4 v128, s[18:19]
	s_add_u32 m0, s11, 0x5000
	s_waitcnt lgkmcnt(6)
	v_mfma_f32_16x16x32_f16 v[104:107], v[230:233], v[186:189], v[104:107]
	v_mfma_f32_16x16x32_f16 v[72:75], v[234:237], v[186:189], v[72:75]
	v_mfma_f32_16x16x32_f16 v[40:43], v[238:241], v[186:189], v[40:43]
	v_mfma_f32_16x16x32_f16 v[8:11], v[242:245], v[186:189], v[8:11]
	global_load_lds_dwordx4 v129, s[18:19]
	s_add_u32 m0, s11, 0x6000
	s_waitcnt lgkmcnt(5)
	v_mfma_f32_16x16x32_f16 v[100:103], v[230:233], v[190:193], v[100:103]
	v_mfma_f32_16x16x32_f16 v[68:71], v[234:237], v[190:193], v[68:71]
	v_mfma_f32_16x16x32_f16 v[36:39], v[238:241], v[190:193], v[36:39]
	v_mfma_f32_16x16x32_f16 v[4:7], v[242:245], v[190:193], v[4:7]
	global_load_lds_dwordx4 v132, s[18:19]
	s_add_u32 m0, s11, 0x7000
	s_waitcnt lgkmcnt(4)
	v_mfma_f32_16x16x32_f16 v[96:99], v[230:233], v[194:197], v[96:99]
	v_mfma_f32_16x16x32_f16 v[64:67], v[234:237], v[194:197], v[64:67]
	v_mfma_f32_16x16x32_f16 v[32:35], v[238:241], v[194:197], v[32:35]
	v_mfma_f32_16x16x32_f16 v[0:3], v[242:245], v[194:197], v[0:3]
	global_load_lds_dwordx4 v133, s[18:19]
	s_waitcnt lgkmcnt(3)
	v_mfma_f32_16x16x32_f16 v[108:111], v[136:139], v[198:201], v[108:111]
	v_mfma_f32_16x16x32_f16 v[76:79], v[140:143], v[198:201], v[76:79]
	v_mfma_f32_16x16x32_f16 v[44:47], v[144:147], v[198:201], v[44:47]
	v_mfma_f32_16x16x32_f16 v[12:15], v[148:151], v[198:201], v[12:15]
	s_waitcnt lgkmcnt(2)
	v_mfma_f32_16x16x32_f16 v[104:107], v[136:139], v[202:205], v[104:107]
	v_mfma_f32_16x16x32_f16 v[72:75], v[140:143], v[202:205], v[72:75]
	v_mfma_f32_16x16x32_f16 v[40:43], v[144:147], v[202:205], v[40:43]
	v_mfma_f32_16x16x32_f16 v[8:11], v[148:151], v[202:205], v[8:11]
	s_waitcnt lgkmcnt(1)
	v_mfma_f32_16x16x32_f16 v[100:103], v[136:139], v[222:225], v[100:103]
	v_mfma_f32_16x16x32_f16 v[68:71], v[140:143], v[222:225], v[68:71]
	v_mfma_f32_16x16x32_f16 v[36:39], v[144:147], v[222:225], v[36:39]
	v_mfma_f32_16x16x32_f16 v[4:7], v[148:151], v[222:225], v[4:7]
	s_waitcnt lgkmcnt(0)
	v_mfma_f32_16x16x32_f16 v[96:99], v[136:139], v[226:229], v[96:99]
	v_mfma_f32_16x16x32_f16 v[64:67], v[140:143], v[226:229], v[64:67]
	v_mfma_f32_16x16x32_f16 v[32:35], v[144:147], v[226:229], v[32:35]
	v_mfma_f32_16x16x32_f16 v[0:3], v[148:151], v[226:229], v[0:3]
	s_add_u32 s18, s18, 128
	s_addc_u32 s19, s19, 0
	s_waitcnt vmcnt(4)
	s_barrier
	ds_read_b128 v[230:233], v175 offset:0
	ds_read_b128 v[182:185], v176 offset:49152
	ds_read_b128 v[234:237], v175 offset:2048
	ds_read_b128 v[238:241], v175 offset:4096
	ds_read_b128 v[242:245], v175 offset:6144
	ds_read_b128 v[136:139], v177 offset:0
	ds_read_b128 v[140:143], v177 offset:2048
	ds_read_b128 v[144:147], v177 offset:4096
	ds_read_b128 v[148:151], v177 offset:6144
	ds_read_b128 v[186:189], v176 offset:51200
	ds_read_b128 v[190:193], v176 offset:53248
	ds_read_b128 v[194:197], v176 offset:55296
	s_waitcnt lgkmcnt(10)
	v_mfma_f32_16x16x32_f16 v[124:127], v[230:233], v[182:185], v[124:127]
	s_waitcnt lgkmcnt(9)
	v_mfma_f32_16x16x32_f16 v[92:95], v[234:237], v[182:185], v[92:95]
	s_waitcnt lgkmcnt(8)
	v_mfma_f32_16x16x32_f16 v[60:63], v[238:241], v[182:185], v[60:63]
	s_waitcnt lgkmcnt(7)
	v_mfma_f32_16x16x32_f16 v[28:31], v[242:245], v[182:185], v[28:31]
	ds_read_b128 v[198:201], v178 offset:49152
	ds_read_b128 v[202:205], v178 offset:51200
	ds_read_b128 v[222:225], v178 offset:53248
	ds_read_b128 v[226:229], v178 offset:55296
	s_waitcnt lgkmcnt(7)
	s_barrier
	s_waitcnt lgkmcnt(6)
	v_mfma_f32_16x16x32_f16 v[120:123], v[230:233], v[186:189], v[120:123]
	v_mfma_f32_16x16x32_f16 v[88:91], v[234:237], v[186:189], v[88:91]
	v_mfma_f32_16x16x32_f16 v[56:59], v[238:241], v[186:189], v[56:59]
	v_mfma_f32_16x16x32_f16 v[24:27], v[242:245], v[186:189], v[24:27]
	s_waitcnt lgkmcnt(5)
	v_mfma_f32_16x16x32_f16 v[116:119], v[230:233], v[190:193], v[116:119]
	v_mfma_f32_16x16x32_f16 v[84:87], v[234:237], v[190:193], v[84:87]
	v_mfma_f32_16x16x32_f16 v[52:55], v[238:241], v[190:193], v[52:55]
	v_mfma_f32_16x16x32_f16 v[20:23], v[242:245], v[190:193], v[20:23]
	s_waitcnt lgkmcnt(4)
	v_mfma_f32_16x16x32_f16 v[112:115], v[230:233], v[194:197], v[112:115]
	v_mfma_f32_16x16x32_f16 v[80:83], v[234:237], v[194:197], v[80:83]
	v_mfma_f32_16x16x32_f16 v[48:51], v[238:241], v[194:197], v[48:51]
	v_mfma_f32_16x16x32_f16 v[16:19], v[242:245], v[194:197], v[16:19]
	s_waitcnt lgkmcnt(3)
	v_mfma_f32_16x16x32_f16 v[124:127], v[136:139], v[198:201], v[124:127]
	v_mfma_f32_16x16x32_f16 v[92:95], v[140:143], v[198:201], v[92:95]
	v_mfma_f32_16x16x32_f16 v[60:63], v[144:147], v[198:201], v[60:63]
	v_mfma_f32_16x16x32_f16 v[28:31], v[148:151], v[198:201], v[28:31]
	s_waitcnt lgkmcnt(2)
	v_mfma_f32_16x16x32_f16 v[120:123], v[136:139], v[202:205], v[120:123]
	v_mfma_f32_16x16x32_f16 v[88:91], v[140:143], v[202:205], v[88:91]
	v_mfma_f32_16x16x32_f16 v[56:59], v[144:147], v[202:205], v[56:59]
	v_mfma_f32_16x16x32_f16 v[24:27], v[148:151], v[202:205], v[24:27]
	s_waitcnt lgkmcnt(1)
	v_mfma_f32_16x16x32_f16 v[116:119], v[136:139], v[222:225], v[116:119]
	v_mfma_f32_16x16x32_f16 v[84:87], v[140:143], v[222:225], v[84:87]
	v_mfma_f32_16x16x32_f16 v[52:55], v[144:147], v[222:225], v[52:55]
	v_mfma_f32_16x16x32_f16 v[20:23], v[148:151], v[222:225], v[20:23]
	s_waitcnt lgkmcnt(0)
	v_mfma_f32_16x16x32_f16 v[112:115], v[136:139], v[226:229], v[112:115]
	v_mfma_f32_16x16x32_f16 v[80:83], v[140:143], v[226:229], v[80:83]
	v_mfma_f32_16x16x32_f16 v[48:51], v[144:147], v[226:229], v[48:51]
	v_mfma_f32_16x16x32_f16 v[16:19], v[148:151], v[226:229], v[16:19]
	s_waitcnt vmcnt(0)
	s_barrier
	ds_read_b128 v[182:185], v176 offset:16384
	ds_read_b128 v[186:189], v176 offset:18432
	ds_read_b128 v[190:193], v176 offset:20480
	ds_read_b128 v[194:197], v176 offset:22528
	ds_read_b128 v[198:201], v178 offset:16384
	ds_read_b128 v[202:205], v178 offset:18432
	ds_read_b128 v[222:225], v178 offset:20480
	ds_read_b128 v[226:229], v178 offset:22528
	s_waitcnt lgkmcnt(7)
	v_mfma_f32_16x16x32_f16 v[108:111], v[230:233], v[182:185], v[108:111]
	v_mfma_f32_16x16x32_f16 v[76:79], v[234:237], v[182:185], v[76:79]
	v_mfma_f32_16x16x32_f16 v[44:47], v[238:241], v[182:185], v[44:47]
	v_mfma_f32_16x16x32_f16 v[12:15], v[242:245], v[182:185], v[12:15]
	s_waitcnt lgkmcnt(6)
	v_mfma_f32_16x16x32_f16 v[104:107], v[230:233], v[186:189], v[104:107]
	v_mfma_f32_16x16x32_f16 v[72:75], v[234:237], v[186:189], v[72:75]
	v_mfma_f32_16x16x32_f16 v[40:43], v[238:241], v[186:189], v[40:43]
	v_mfma_f32_16x16x32_f16 v[8:11], v[242:245], v[186:189], v[8:11]
	s_waitcnt lgkmcnt(5)
	v_mfma_f32_16x16x32_f16 v[100:103], v[230:233], v[190:193], v[100:103]
	v_mfma_f32_16x16x32_f16 v[68:71], v[234:237], v[190:193], v[68:71]
	v_mfma_f32_16x16x32_f16 v[36:39], v[238:241], v[190:193], v[36:39]
	v_mfma_f32_16x16x32_f16 v[4:7], v[242:245], v[190:193], v[4:7]
	s_waitcnt lgkmcnt(4)
	v_mfma_f32_16x16x32_f16 v[96:99], v[230:233], v[194:197], v[96:99]
	v_mfma_f32_16x16x32_f16 v[64:67], v[234:237], v[194:197], v[64:67]
	v_mfma_f32_16x16x32_f16 v[32:35], v[238:241], v[194:197], v[32:35]
	v_mfma_f32_16x16x32_f16 v[0:3], v[242:245], v[194:197], v[0:3]
	s_waitcnt lgkmcnt(3)
	v_mfma_f32_16x16x32_f16 v[108:111], v[136:139], v[198:201], v[108:111]
	v_mfma_f32_16x16x32_f16 v[76:79], v[140:143], v[198:201], v[76:79]
	v_mfma_f32_16x16x32_f16 v[44:47], v[144:147], v[198:201], v[44:47]
	v_mfma_f32_16x16x32_f16 v[12:15], v[148:151], v[198:201], v[12:15]
	s_waitcnt lgkmcnt(2)
	v_mfma_f32_16x16x32_f16 v[104:107], v[136:139], v[202:205], v[104:107]
	v_mfma_f32_16x16x32_f16 v[72:75], v[140:143], v[202:205], v[72:75]
	v_mfma_f32_16x16x32_f16 v[40:43], v[144:147], v[202:205], v[40:43]
	v_mfma_f32_16x16x32_f16 v[8:11], v[148:151], v[202:205], v[8:11]
	s_waitcnt lgkmcnt(1)
	v_mfma_f32_16x16x32_f16 v[100:103], v[136:139], v[222:225], v[100:103]
	v_mfma_f32_16x16x32_f16 v[68:71], v[140:143], v[222:225], v[68:71]
	v_mfma_f32_16x16x32_f16 v[36:39], v[144:147], v[222:225], v[36:39]
	v_mfma_f32_16x16x32_f16 v[4:7], v[148:151], v[222:225], v[4:7]
	s_waitcnt lgkmcnt(0)
	v_mfma_f32_16x16x32_f16 v[96:99], v[136:139], v[226:229], v[96:99]
	v_mfma_f32_16x16x32_f16 v[64:67], v[140:143], v[226:229], v[64:67]
	v_mfma_f32_16x16x32_f16 v[32:35], v[144:147], v[226:229], v[32:35]
	v_mfma_f32_16x16x32_f16 v[0:3], v[148:151], v[226:229], v[0:3]
	s_nop 7
	s_cmpk_lt_u32 s9, 0x620
	s_cbranch_scc0 .Lgin_cls_lat
	s_cmp_lt_u32 s16, 4
	s_cbranch_scc1 .Lgin_plain
	s_sub_u32 s4, s16, 8
	s_cmp_lt_u32 s4, 28
	s_cbranch_scc1 .Lgin_plain
	s_sub_u32 s4, s16, 45
	s_cmp_lt_u32 s4, 3
	s_cbranch_scc1 .Lgin_plain
	s_sub_u32 s4, s16, 4
	s_cmp_lt_u32 s4, 2
	s_cbranch_scc1 .Lgin_kvar
	s_sub_u32 s4, s16, 37
	s_cmp_lt_u32 s4, 3
	s_cbranch_scc1 .Lgin_kvar
	s_sub_u32 s4, s16, 6
	s_cmp_lt_u32 s4, 2
	s_cbranch_scc1 .Lgin_vvar
	s_sub_u32 s4, s16, 41
	s_cmp_lt_u32 s4, 3
	s_cbranch_scc1 .Lgin_vvar
	s_branch .Lgin_notplain
